# NSA window loop: ALiBi key term via QK accumulator C input + stepped row term (52 VALU/iter removed), hoisted mask adds back in masked path, 4 KB extra static LDS parks one idle register quad; selecte
# speedup vs baseline: 1.1312x; 1.0104x over previous
; __device__ void item_nsa(const Params& p, int layer, int b, int g, int qt, unsigned char* smem) {
;     ...
;     flash_pass<false, 1, 2, 2>(hb + C_KW + g * 64, HS, vt, SEQ, wkb, wke, 0u, qf, tq, q0, q0 + 31, slope2[0], 512, allsel, c1, O, l, sK, sVt, sel_hook);
;     __syncthreads();
; #pragma unroll
;     for (int n = 0; n < 2; ++n) {
;       float inv = gate[n][2] / l[n];
; #pragma unroll
;       for (int dt = 0; dt < 4; ++dt) {
;         float a0 = Of[n][dt][0] + O[n][dt][0] * inv, a1 = Of[n][dt][1] + O[n][dt][1] * inv;
;         float a2 = Of[n][dt][2] + O[n][dt][2] * inv, a3 = Of[n][dt][3] + O[n][dt][3] * inv;
;         uint2 o; o.x = pack2(a0, a1); o.y = pack2(a2, a3);
;         *(uint2*)(sOf + n * 16 * 72 + dt * 16) = o;
;       }
;     }
;   }
.Lwin_exit:
	v_lshlrev_b32_e32 v0, 4, v210
	v_add_u32_e32 v0, 0x12110, v0
	ds_read_b128 v[48:51], v0
	s_waitcnt lgkmcnt(0)
	s_branch .LBB0_128

;     ...
;         for (int n = 0; n < NQ; ++n) {
;           f32x4 S[4];
; #pragma unroll
;           for (int mt = 0; mt < 4; ++mt) S[mt] = f32x4{0.f, 0.f, 0.f, 0.f};
; #pragma unroll
;           for (int ks = 0; ks < 2; ++ks) {
;             if (NMAP == 2 && ks != mp) continue;
; #pragma unroll
;             for (int mt = 0; mt < 4; ++mt) {
;               bf16x8 a = *(const bf16x8*)(cK + (mt * 16 + l15) * 64 + (((ks * 4 + quad) ^ ((l15 >> 1) & 7)) * 8));
;               S[mt] = mfma16(a, qf[n][ks], S[mt]);
;             }
;           }
;           bf16x8 pb[2];
;           const float tb = slope2 * (float)(kbase - tq[n]);
;           if (full || rowfull) {
;             sm_step<false>(S, c1, slope2, tb, kbase, tq[n], window, true, pb);
;             if (SEL && !full && !selok[n]) {
;               pb[0] = bf16x8{0, 0, 0, 0, 0, 0, 0, 0}; pb[1] = bf16x8{0, 0, 0, 0, 0, 0, 0, 0};
;             }
;           } else sm_step<true>(S, c1, slope2, tb, kbase, tq[n], window, selok[n], pb);
; #pragma unroll
;           for (int k2 = 0; k2 < 2; ++k2) {
; #pragma unroll
;             for (int dt = 0; dt < 4; ++dt) {
;               bf16x8 a = vt_frag(cV, dt, k2, l15, quad);
;               O[mp * NQ + n][dt] = mfma16(a, pb[k2], O[mp * NQ + n][dt]);
;             }
;             L[mp * NQ + n] = mfma16(ones, pb[k2], L[mp * NQ + n]);
;           }
.LBB0_147:
	v_lshlrev_b32_e32 v2, 1, v154
	v_add3_u32 v2, s29, v2, v156
	v_add_u32_e32 v3, 0x2000, v2
	v_add_u32_e32 v128, 0x2800, v2
	v_add_u32_e32 v132, 0x3000, v2
	v_add_u32_e32 v2, 0x3800, v2
	ds_read2_b64 v[88:91], v3 offset0:128 offset1:132
	ds_read2_b64 v[100:103], v128 offset0:160 offset1:164
	ds_read2_b64 v[116:119], v132 offset0:192 offset1:196
	ds_read2_b64 v[120:123], v2 offset0:224 offset1:228
	s_mov_b32 s30, s28
	s_mov_b32 s31, s28
	s_mov_b32 s29, s28
	v_mov_b64_e32 v[162:163], s[30:31]
	v_mov_b64_e32 v[160:161], s[28:29]
	s_waitcnt lgkmcnt(3)
	v_mfma_f32_16x16x32_bf16 v[52:55], v[88:91], v[124:127], v[52:55]
	ds_read2_b64 v[128:131], v128 offset0:168 offset1:172
	ds_read2_b64 v[132:135], v132 offset0:200 offset1:204
	ds_read2_b64 v[136:139], v2 offset0:232 offset1:236
	s_waitcnt lgkmcnt(5)
	v_mfma_f32_16x16x32_bf16 v[48:51], v[100:103], v[124:127], v[48:51]
	s_mov_b64 s[30:31], -1
	s_andn2_b64 vcc, exec, s[42:43]
	s_waitcnt lgkmcnt(4)
	v_mfma_f32_16x16x32_bf16 v[44:47], v[116:119], v[124:127], v[44:47]
	s_waitcnt lgkmcnt(3)
	v_mfma_f32_16x16x32_bf16 v[40:43], v[120:123], v[124:127], v[40:43]
	v_mfma_f32_16x16x32_bf16 v[56:59], v[160:163], v[124:127], v[56:59]
	ds_read2_b64 v[124:127], v3 offset0:136 offset1:140
	v_mfma_f32_16x16x32_bf16 v[76:79], v[76:79], v[12:15], v[230:233]
	v_mfma_f32_16x16x32_bf16 v[80:83], v[80:83], v[12:15], v[234:237]
	v_mfma_f32_16x16x32_bf16 v[84:87], v[84:87], v[12:15], v[242:245]
	v_mfma_f32_16x16x32_bf16 v[92:95], v[92:95], v[12:15], v[246:249]
	v_mfma_f32_16x16x32_bf16 v[96:99], v[96:99], v[16:19], v[76:79]
	s_nop 3
	v_sub_u32_e32 v76, v0, v201
	v_cvt_f32_i32_e32 v2, v76
	v_mfma_f32_16x16x32_bf16 v[78:81], v[104:107], v[16:19], v[80:83]
	v_mul_f32_e32 v2, v188, v2
	v_mfma_f32_16x16x32_bf16 v[104:107], v[108:111], v[16:19], v[84:87]
	v_fmamk_f32 v3, v96, 0x3e38aa3b, v2
	v_fmamk_f32 v77, v97, 0x3e38aa3b, v2
	s_nop 0
	v_mfma_f32_16x16x32_bf16 v[108:111], v[112:115], v[16:19], v[92:95]
	v_fmamk_f32 v84, v98, 0x3e38aa3b, v2
	v_fmamk_f32 v85, v99, 0x3e38aa3b, v2
	v_fmamk_f32 v86, v78, 0x3e38aa3b, v2
	s_waitcnt lgkmcnt(0)
	v_mfma_f32_16x16x32_bf16 v[52:55], v[124:127], v[140:143], v[52:55]
	v_fmamk_f32 v87, v79, 0x3e38aa3b, v2
	v_fmamk_f32 v92, v80, 0x3e38aa3b, v2
	v_fmamk_f32 v93, v81, 0x3e38aa3b, v2
	v_mfma_f32_16x16x32_bf16 v[48:51], v[128:131], v[140:143], v[48:51]
	v_fmamk_f32 v94, v104, 0x3e38aa3b, v2
	v_fmamk_f32 v95, v105, 0x3e38aa3b, v2
	v_fmamk_f32 v96, v106, 0x3e38aa3b, v2
	v_mfma_f32_16x16x32_bf16 v[44:47], v[132:135], v[140:143], v[44:47]
	v_fmamk_f32 v97, v107, 0x3e38aa3b, v2
	v_fmamk_f32 v98, v108, 0x3e38aa3b, v2
	v_fmamk_f32 v99, v109, 0x3e38aa3b, v2
	v_mfma_f32_16x16x32_bf16 v[40:43], v[136:139], v[140:143], v[40:43]
	v_fmamk_f32 v104, v110, 0x3e38aa3b, v2
	v_fmac_f32_e32 v2, 0x3e38aa3b, v111
	v_mov_b32_e32 v105, v77
	v_mfma_f32_16x16x32_bf16 v[56:59], v[160:163], v[140:143], v[56:59]
	s_cbranch_vccnz .LBB0_149
	v_sub_u32_e32 v0, v201, v0
	v_cmp_gt_u32_e32 vcc, s26, v0
	s_and_b64 vcc, s[38:39], vcc
	v_add_u32_e32 v78, -2, v0
	v_cndmask_b32_e32 v77, v226, v3, vcc
	v_cmp_lt_u32_e32 vcc, s34, v76
	s_and_b64 vcc, s[38:39], vcc
	v_add_u32_e32 v79, -3, v0
	v_cndmask_b32_e32 v76, v226, v105, vcc
	v_cmp_gt_u32_e32 vcc, s26, v78
	s_and_b64 vcc, s[38:39], vcc
	v_add_u32_e32 v80, -16, v0
	v_cndmask_b32_e32 v78, v226, v84, vcc
	v_cmp_gt_u32_e32 vcc, s26, v79
	s_and_b64 vcc, s[38:39], vcc
	v_exp_f32_e32 v77, v77
	v_cndmask_b32_e32 v79, v226, v85, vcc
	v_cmp_gt_u32_e32 vcc, s26, v80
	s_and_b64 vcc, s[38:39], vcc
	v_exp_f32_e32 v76, v76
	v_cndmask_b32_e32 v80, v226, v86, vcc
	v_exp_f32_e32 v82, v80
	v_subrev_u32_e32 v80, 17, v0
	v_cmp_gt_u32_e32 vcc, s26, v80
	s_and_b64 vcc, s[38:39], vcc
	v_exp_f32_e32 v78, v78
	v_cndmask_b32_e32 v80, v226, v87, vcc
	v_exp_f32_e32 v83, v80
	v_subrev_u32_e32 v80, 18, v0
	v_cmp_gt_u32_e32 vcc, s26, v80
	s_and_b64 vcc, s[38:39], vcc
	v_exp_f32_e32 v79, v79
	v_cndmask_b32_e32 v80, v226, v92, vcc
	v_exp_f32_e32 v106, v80
	v_subrev_u32_e32 v80, 19, v0
	v_cmp_gt_u32_e32 vcc, s26, v80
	s_and_b64 vcc, s[38:39], vcc
	v_cvt_pk_bf16_f32 v81, v78, v79
	v_cndmask_b32_e32 v80, v226, v93, vcc
	v_exp_f32_e32 v107, v80
	v_subrev_u32_e32 v80, 32, v0
	v_cmp_gt_u32_e32 vcc, s26, v80
	s_and_b64 vcc, s[38:39], vcc
	v_cvt_pk_bf16_f32 v82, v82, v83
	v_cndmask_b32_e32 v80, v226, v94, vcc
	v_exp_f32_e32 v108, v80
	v_subrev_u32_e32 v80, 33, v0
	v_cmp_gt_u32_e32 vcc, s26, v80
	s_and_b64 vcc, s[38:39], vcc
	v_cvt_pk_bf16_f32 v83, v106, v107
	v_cndmask_b32_e32 v80, v226, v95, vcc
	v_exp_f32_e32 v109, v80
	v_subrev_u32_e32 v80, 34, v0
	v_cmp_gt_u32_e32 vcc, s26, v80
	s_and_b64 vcc, s[38:39], vcc
	s_mov_b64 s[30:31], 0
	v_cndmask_b32_e32 v80, v226, v96, vcc
	v_exp_f32_e32 v110, v80
	v_subrev_u32_e32 v80, 35, v0
	v_cmp_gt_u32_e32 vcc, s26, v80
	s_and_b64 vcc, s[38:39], vcc
	s_nop 0
	v_cndmask_b32_e32 v80, v226, v97, vcc
	v_exp_f32_e32 v111, v80
	v_subrev_u32_e32 v80, 48, v0
	v_cmp_gt_u32_e32 vcc, s26, v80
	s_and_b64 vcc, s[38:39], vcc
	s_nop 0
	v_cndmask_b32_e32 v80, v226, v98, vcc
	v_exp_f32_e32 v112, v80
	v_subrev_u32_e32 v80, 49, v0
	v_cmp_gt_u32_e32 vcc, s26, v80
	s_and_b64 vcc, s[38:39], vcc
	s_nop 0
	v_cndmask_b32_e32 v80, v226, v99, vcc
	v_exp_f32_e32 v113, v80
	v_subrev_u32_e32 v80, 50, v0
	v_cmp_gt_u32_e32 vcc, s26, v80
	s_and_b64 vcc, s[38:39], vcc
	v_subrev_u32_e32 v0, 51, v0
	v_cndmask_b32_e32 v80, v226, v104, vcc
	v_cmp_gt_u32_e32 vcc, s26, v0
	s_and_b64 vcc, s[38:39], vcc
	v_exp_f32_e32 v114, v80
	v_cndmask_b32_e32 v0, v226, v2, vcc
	v_exp_f32_e32 v0, v0
	v_cvt_pk_bf16_f32 v80, v77, v76
	v_cvt_pk_bf16_f32 v76, v108, v109
	v_cvt_pk_bf16_f32 v77, v110, v111
	v_cvt_pk_bf16_f32 v78, v112, v113
	v_cvt_pk_bf16_f32 v79, v114, v0

;     ...
;   const bf16x8 ones = bf16x8{0x3F80, 0x3F80, 0x3F80, 0x3F80, 0x3F80, 0x3F80, 0x3F80, 0x3F80};
;   f32x4 L[NQ * NMAP];
; #pragma unroll
;   for (int i = 0; i < NQ * NMAP; ++i) L[i] = f32x4{0.f, 0.f, 0.f, 0.f};
;   int nxt = next_tile(kt);
;   {
;     u32x4 fk[TK][2], fv[TK][2];
; #pragma unroll
;     for (int t = 0; t < TK; ++t)
; #pragma unroll
;       for (int i = 0; i < 2; ++i) {
;         fk[t][i] = *(const u32x4*)(gk + (size_t)((kt + t) * 64 + i * 32) * kstride);
;         fv[t][i] = *(const u32x4*)(gv + (size_t)(i * 32) * vtstride + (kt + t) * 64);
;       }
;     if (nxt < kt_end) gload(nxt);
;     hook();
;     __syncthreads();
; #pragma unroll
;     for (int t = 0; t < TK; ++t)
; #pragma unroll
;       for (int i = 0; i < 2; ++i) {
;         *(u32x4*)(wk + t * TSZ + i * 32 * 64) = fk[t][i];
;         *(u32x4*)(wv + t * TSZ + i * 32 * 72) = fv[t][i];
;       }
;   }
;   __syncthreads();
;   int stg = 0;
; __device__ void item_nsa(const Params& p, int layer, int b, int g, int qt, unsigned char* smem) {
;     ...
;     int lo = q0 - 511; if (lo < 0) lo = 0;
;     const unsigned allsel[2] = {0xffffffffu, 0xffffffffu};
;     int wkb = lo >> 6, wke = kt_end;
;     ...
;     flash_pass<false, 1, 2, 2>(hb + C_KW + g * 64, HS, vt, SEQ, wkb, wke, 0u, qf, tq, q0, q0 + 31, slope2[0], 512, allsel, c1, O, l, sK, sVt, sel_hook);
.LBB0_161:
	s_or_b64 exec, exec, s[0:1]
	v_lshlrev_b32_e32 v122, 2, v120
	v_lshrrev_b32_e32 v3, 4, v121
	v_or_b32_e32 v123, 0x12000, v122
	v_or_b32_e32 v122, 0x12040, v122
	v_xor_b32_e32 v119, v3, v121
	s_waitcnt lgkmcnt(0)
	s_barrier
	ds_read_b32 v207, v123
	ds_read_b32 v208, v122
	ds_read_b32 v122, v212
	v_lshlrev_b32_e32 v117, 7, v118
	v_lshlrev_b32_e32 v119, 4, v119
	s_movk_i32 s0, 0x70
	v_lshlrev_b32_e32 v118, 4, v118
	v_and_b32_e32 v2, 15, v121
	v_bfe_u32 v116, v121, 4, 2
	v_and_or_b32 v209, v119, s0, v117
	v_add3_u32 v230, v117, v118, v0
	s_mov_b64 s[0:1], 0x20000
	v_bfe_u32 v0, v121, 1, 3
	v_lshl_add_u64 v[198:199], v[196:197], 0, s[0:1]
	v_lshlrev_b32_e32 v231, 2, v116
	v_lshlrev_b32_e32 v232, 7, v2
	v_mul_u32_u24_e32 v233, 0x90, v2
	v_bitop3_b32 v2, v3, v0, 3 bitop3:0x6c
	v_bitop3_b32 v0, v116, v0, 4 bitop3:0x36
	s_lshl_b32 s0, s29, 5
	v_lshlrev_b32_e32 v234, 4, v2
	v_lshlrev_b32_e32 v235, 4, v0
	v_or_b32_e32 v0, s0, v231
	v_mov_b32_e32 v2, v1
	v_mov_b32_e32 v3, v1
	s_waitcnt lgkmcnt(0)
	v_readfirstlane_b32 s46, v122
	s_barrier
	s_waitcnt vmcnt(7)
	ds_write_b128 v209, v[88:91]
	s_waitcnt vmcnt(5)
	ds_write_b128 v230, v[96:99] offset:9216
	ds_write_b128 v209, v[84:87] offset:4096
	s_waitcnt vmcnt(1)
	ds_write_b128 v230, v[112:115] offset:13824
	ds_write_b128 v209, v[104:107] offset:18432
	ds_write_b128 v230, v[92:95] offset:27648
	ds_write_b128 v209, v[100:103] offset:22528
	s_waitcnt vmcnt(0)
	ds_write_b128 v230, v[108:111] offset:32256
	s_add_i32 s1, s0, s86
	v_sub_u32_e32 v236, v120, v231
	v_sub_u32_e32 v237, v0, v120
	v_mov_b32_e32 v0, v1
	v_mov_b64_e32 v[86:87], v[2:3]
	v_mov_b64_e32 v[90:91], v[2:3]
	v_mov_b64_e32 v[98:99], v[2:3]
	v_mov_b64_e32 v[102:103], v[2:3]
	v_mov_b64_e32 v[106:107], v[2:3]
	v_mov_b64_e32 v[118:119], v[2:3]
	v_mov_b64_e32 v[122:123], v[2:3]
	v_mov_b64_e32 v[114:115], v[2:3]
	v_mov_b64_e32 v[110:111], v[2:3]
	v_mov_b64_e32 v[94:95], v[2:3]
	s_add_i32 s40, s86, 0x7f
	s_sub_i32 s41, 0x7ff, s1
	s_mov_b32 s42, 0
	v_mov_b64_e32 v[84:85], v[0:1]
	v_mov_b64_e32 v[88:89], v[0:1]
	v_mov_b64_e32 v[96:97], v[0:1]
	v_mov_b64_e32 v[100:101], v[0:1]
	v_mov_b64_e32 v[104:105], v[0:1]
	v_mov_b64_e32 v[116:117], v[0:1]
	v_mov_b64_e32 v[120:121], v[0:1]
	v_mov_b64_e32 v[112:113], v[0:1]
	v_mov_b64_e32 v[108:109], v[0:1]
	v_mov_b64_e32 v[92:93], v[0:1]
	s_movk_i32 s75, 0x210
	s_mov_b32 s77, 0x40000
	s_mov_b32 s78, 0x60000
	s_waitcnt lgkmcnt(0)
	s_barrier
	v_lshlrev_b32_e32 v0, 4, v210
	v_add_u32_e32 v0, 0x12110, v0
	ds_write_b128 v0, v[48:51]
	v_mul_f32_e32 v49, 0x40b17218, v188
	v_mul_f32_e32 v50, 2.0, v49
	v_mul_f32_e32 v51, 0x40400000, v49
	v_mov_b32_e32 v48, 0

; __device__ __forceinline__ float fexp2(float x) { return __builtin_amdgcn_exp2f(x); }
; template <bool MASKED>
; __device__ __forceinline__ void sm_step(f32x4 (&S)[4], float c1, float slope2, float tb, int kbase, int tqn,
;                                         int window, bool selok, bf16x8 (&pb)[2]) {
; #pragma unroll
;   for (int mt = 0; mt < 4; ++mt)
; #pragma unroll
;     for (int r = 0; r < 4; ++r) {
;       float u = fmaf(slope2, (float)(mt * 16 + r), fmaf(S[mt][r], c1, tb));
;       if (MASKED) {
;         int dist = tqn - (kbase + mt * 16 + r);
;         bool valid = (dist >= 0) && (dist < window) && selok;
;         u = valid ? u : -1e30f;
;       }
;       S[mt][r] = fexp2(u);
;     }
;     ...
; #pragma unroll
;       for (int mp = 0; mp < NMAP; ++mp) {
; #pragma unroll
;         for (int n = 0; n < NQ; ++n) {
;           f32x4 S[4];
; #pragma unroll
;           for (int mt = 0; mt < 4; ++mt) S[mt] = f32x4{0.f, 0.f, 0.f, 0.f};
; #pragma unroll
;           for (int ks = 0; ks < 2; ++ks) {
;             if (NMAP == 2 && ks != mp) continue;
; #pragma unroll
;             for (int mt = 0; mt < 4; ++mt) {
;               bf16x8 a = *(const bf16x8*)(cK + (mt * 16 + l15) * 64 + (((ks * 4 + quad) ^ ((l15 >> 1) & 7)) * 8));
;               S[mt] = mfma16(a, qf[n][ks], S[mt]);
;             }
;           }
;           bf16x8 pb[2];
;           const float tb = slope2 * (float)(kbase - tq[n]);
;           if (full || rowfull) {
;             sm_step<false>(S, c1, slope2, tb, kbase, tq[n], window, true, pb);
;             if (SEL && !full && !selok[n]) {
;               pb[0] = bf16x8{0, 0, 0, 0, 0, 0, 0, 0}; pb[1] = bf16x8{0, 0, 0, 0, 0, 0, 0, 0};
;             }
;           } else sm_step<true>(S, c1, slope2, tb, kbase, tq[n], window, selok[n], pb);
.LBB0_166:
	s_add_i32 s24, s40, 0xffffff81
	s_cmp_gt_i32 s24, s12
	s_mul_i32 s24, s42, 0x9000
	s_cbranch_scc1 .LBB0_177
	s_add_i32 s29, s41, 0xffffffa2
	s_cmpk_gt_i32 s29, 0x1ff
	s_cbranch_scc1 .LBB0_177
	v_add_u32_e32 v0, s24, v232
	v_add_u32_e32 v2, v0, v234
	v_add_u32_e32 v0, v0, v235
	ds_read_b128 v[148:151], v2
	ds_read_b128 v[132:135], v2 offset:2048
	ds_read_b128 v[152:155], v0
	ds_read_b128 v[144:147], v0 offset:2048
	s_waitcnt lgkmcnt(3)
	v_mfma_f32_16x16x32_bf16 v[136:139], v[148:151], v[4:7], v[48:51]
	ds_read_b128 v[128:131], v2 offset:4096
	ds_read_b128 v[124:127], v2 offset:6144
	ds_read_b128 v[140:143], v0 offset:4096
	s_waitcnt lgkmcnt(4)
	v_mfma_f32_16x16x32_bf16 v[168:171], v[152:155], v[8:11], v[136:139]
	s_sub_i32 s29, s40, 64
	s_nop 1
	ds_read_b128 v[136:139], v0 offset:6144
	v_add_u32_e32 v0, s40, v237
	v_mfma_f32_16x16x32_bf16 v[156:159], v[132:135], v[4:7], v[48:51]
	v_add_u32_e32 v172, 0xfffff7a1, v0
	v_cvt_f32_i32_e32 v2, v172
	s_cmpk_gt_i32 s41, 0x1ff
	s_waitcnt lgkmcnt(3)
	v_mfma_f32_16x16x32_bf16 v[160:163], v[128:131], v[4:7], v[48:51]
	s_cselect_b64 s[30:31], -1, 0
	s_cmp_gt_i32 s29, s8
	s_cselect_b64 s[38:39], -1, 0
	s_waitcnt lgkmcnt(2)
	v_mfma_f32_16x16x32_bf16 v[164:167], v[124:127], v[4:7], v[48:51]
	s_or_b64 s[38:39], s[38:39], s[30:31]
	s_mov_b64 s[30:31], -1
	s_and_b64 vcc, exec, s[38:39]
	v_mfma_f32_16x16x32_bf16 v[174:177], v[144:147], v[8:11], v[156:159]
	s_waitcnt lgkmcnt(1)
	v_mfma_f32_16x16x32_bf16 v[158:161], v[140:143], v[8:11], v[160:163]
	s_nop 0
	v_mul_f32_e32 v156, v188, v2
	v_fmamk_f32 v157, v168, 0x3e38aa3b, v156
	v_fmamk_f32 v2, v169, 0x3e38aa3b, v156
	s_waitcnt lgkmcnt(0)
	v_mfma_f32_16x16x32_bf16 v[178:181], v[136:139], v[8:11], v[164:167]
	v_fmamk_f32 v163, v170, 0x3e38aa3b, v156
	s_nop 1
	v_fmamk_f32 v164, v171, 0x3e38aa3b, v156
	v_fmac_f32_e32 v156, 0x41800000, v188
	v_fmamk_f32 v168, v177, 0x3e38aa3b, v156
	v_fmamk_f32 v165, v174, 0x3e38aa3b, v156
	v_fmamk_f32 v166, v175, 0x3e38aa3b, v156
	v_fmamk_f32 v167, v176, 0x3e38aa3b, v156
	v_fmac_f32_e32 v156, 0x41800000, v188
	v_fmamk_f32 v169, v158, 0x3e38aa3b, v156
	v_fmamk_f32 v170, v159, 0x3e38aa3b, v156
	v_fmamk_f32 v159, v160, 0x3e38aa3b, v156
	v_fmamk_f32 v160, v161, 0x3e38aa3b, v156
	v_fmac_f32_e32 v156, 0x41800000, v188
	v_fmamk_f32 v161, v178, 0x3e38aa3b, v156
	v_fmamk_f32 v162, v179, 0x3e38aa3b, v156
	v_fmamk_f32 v158, v180, 0x3e38aa3b, v156
	v_fmac_f32_e32 v156, 0x3e38aa3b, v181
	v_mov_b32_e32 v171, v2
	s_cbranch_vccz .LBB0_170
	v_add_u32_e32 v173, s41, v236
	v_subrev_u32_e32 v2, 31, v173
	v_cmp_gt_u32_e32 vcc, s10, v2
	v_subrev_u32_e32 v3, 64, v173
	v_add_u32_e32 v176, 0xffffffbf, v173
	v_cndmask_b32_e32 v2, v226, v157, vcc
	v_cmp_lt_u32_e32 vcc, s13, v172
	v_exp_f32_e32 v174, v2
	s_mov_b64 s[30:31], 0
	v_cndmask_b32_e32 v2, v226, v171, vcc
	v_exp_f32_e32 v172, v2
	v_subrev_u32_e32 v2, 33, v173
	v_cmp_gt_u32_e32 vcc, s10, v2
	s_nop 1
	v_cndmask_b32_e32 v2, v226, v163, vcc
	v_exp_f32_e32 v175, v2
	v_subrev_u32_e32 v2, 34, v173
	v_cmp_gt_u32_e32 vcc, s10, v2
	s_nop 1
	v_cndmask_b32_e32 v2, v226, v164, vcc
	v_exp_f32_e32 v177, v2
	v_subrev_u32_e32 v2, 47, v173
	v_cmp_gt_u32_e32 vcc, s10, v2
	v_cvt_pk_bf16_f32 v177, v175, v177
	s_nop 0
	v_cndmask_b32_e32 v2, v226, v165, vcc
	v_exp_f32_e32 v178, v2
	v_subrev_u32_e32 v2, 48, v173
	v_cmp_gt_u32_e32 vcc, s10, v2
	s_nop 1
	v_cndmask_b32_e32 v2, v226, v166, vcc
	v_exp_f32_e32 v179, v2
	v_subrev_u32_e32 v2, 49, v173
	v_cmp_gt_u32_e32 vcc, s10, v2
	v_cvt_pk_bf16_f32 v178, v178, v179
	s_nop 0
	v_cndmask_b32_e32 v2, v226, v167, vcc
	v_exp_f32_e32 v186, v2
	v_subrev_u32_e32 v2, 50, v173
	v_cmp_gt_u32_e32 vcc, s10, v2
	s_nop 1
	v_cndmask_b32_e32 v2, v226, v168, vcc
	v_exp_f32_e32 v187, v2
	v_subrev_u32_e32 v2, 63, v173
	v_cmp_gt_u32_e32 vcc, s10, v2
	v_cvt_pk_bf16_f32 v179, v186, v187
	s_nop 0
	v_cndmask_b32_e32 v2, v226, v169, vcc
	v_cmp_gt_u32_e32 vcc, s10, v3
	v_exp_f32_e32 v2, v2
	s_nop 0
	v_cndmask_b32_e32 v3, v226, v170, vcc
	v_cmp_gt_u32_e32 vcc, s10, v176
	v_exp_f32_e32 v3, v3
	s_nop 0
	v_cndmask_b32_e32 v176, v226, v159, vcc
	v_exp_f32_e32 v180, v176
	v_add_u32_e32 v176, 0xffffffbe, v173
	v_cmp_gt_u32_e32 vcc, s10, v176
	s_nop 1
	v_cndmask_b32_e32 v176, v226, v160, vcc
	v_exp_f32_e32 v181, v176
	v_add_u32_e32 v176, 0xffffffb1, v173
	v_cmp_gt_u32_e32 vcc, s10, v176
	s_nop 1
	v_cndmask_b32_e32 v176, v226, v161, vcc
	v_exp_f32_e32 v182, v176
	v_add_u32_e32 v176, 0xffffffb0, v173
	v_cmp_gt_u32_e32 vcc, s10, v176
	s_nop 1
	v_cndmask_b32_e32 v176, v226, v162, vcc
	v_exp_f32_e32 v183, v176
	v_add_u32_e32 v176, 0xffffffaf, v173
	v_cmp_gt_u32_e32 vcc, s10, v176
	v_add_u32_e32 v173, 0xffffffae, v173
	s_nop 0
	v_cndmask_b32_e32 v176, v226, v158, vcc
	v_cmp_gt_u32_e32 vcc, s10, v173
	v_exp_f32_e32 v184, v176
	v_cvt_pk_bf16_f32 v176, v174, v172
	v_cndmask_b32_e32 v173, v226, v156, vcc
	v_exp_f32_e32 v185, v173

;     ...
;         for (int n = 0; n < NQ; ++n) {
;           f32x4 S[4];
; #pragma unroll
;           for (int mt = 0; mt < 4; ++mt) S[mt] = f32x4{0.f, 0.f, 0.f, 0.f};
; #pragma unroll
;           for (int ks = 0; ks < 2; ++ks) {
;             if (NMAP == 2 && ks != mp) continue;
; #pragma unroll
;             for (int mt = 0; mt < 4; ++mt) {
;               bf16x8 a = *(const bf16x8*)(cK + (mt * 16 + l15) * 64 + (((ks * 4 + quad) ^ ((l15 >> 1) & 7)) * 8));
;               S[mt] = mfma16(a, qf[n][ks], S[mt]);
;             }
;           }
;           bf16x8 pb[2];
;           const float tb = slope2 * (float)(kbase - tq[n]);
;           if (full || rowfull) {
;             sm_step<false>(S, c1, slope2, tb, kbase, tq[n], window, true, pb);
;             if (SEL && !full && !selok[n]) {
;               pb[0] = bf16x8{0, 0, 0, 0, 0, 0, 0, 0}; pb[1] = bf16x8{0, 0, 0, 0, 0, 0, 0, 0};
;             }
;           } else sm_step<true>(S, c1, slope2, tb, kbase, tq[n], window, selok[n], pb);
; #pragma unroll
;           for (int k2 = 0; k2 < 2; ++k2) {
; #pragma unroll
;             for (int dt = 0; dt < 4; ++dt) {
;               bf16x8 a = vt_frag(cV, dt, k2, l15, quad);
;               O[mp * NQ + n][dt] = mfma16(a, pb[k2], O[mp * NQ + n][dt]);
;             }
;             L[mp * NQ + n] = mfma16(ones, pb[k2], L[mp * NQ + n]);
;           }
.LBB0_172:
	v_lshlrev_b32_e32 v156, 1, v231
	v_add3_u32 v168, s24, v156, v233
	v_add_u32_e32 v169, 0x2000, v168
	v_add_u32_e32 v186, 0x2800, v168
	v_add_u32_e32 v218, 0x3000, v168
	v_add_u32_e32 v219, 0x3800, v168
	ds_read2_b64 v[156:159], v169 offset0:128 offset1:132
	ds_read2_b64 v[160:163], v186 offset0:160 offset1:164
	ds_read2_b64 v[164:167], v218 offset0:192 offset1:196
	ds_read2_b64 v[172:175], v219 offset0:224 offset1:228
	s_mov_b32 s30, s28
	s_mov_b32 s31, s28
	s_mov_b32 s29, s28
	v_mov_b64_e32 v[240:241], s[30:31]
	v_mov_b64_e32 v[238:239], s[28:29]
	s_waitcnt lgkmcnt(3)
	v_mfma_f32_16x16x32_bf16 v[112:115], v[156:159], v[176:179], v[112:115]
	v_cvt_pk_bf16_f32 v245, v184, v185
	ds_read2_b64 v[168:171], v169 offset0:136 offset1:140
	v_cvt_pk_bf16_f32 v244, v182, v183
	s_waitcnt lgkmcnt(3)
	v_mfma_f32_16x16x32_bf16 v[120:123], v[160:163], v[176:179], v[120:123]
	v_add_u32_e32 v183, 0xfffff791, v0
	v_cvt_f32_i32_e32 v0, v183
	v_cvt_pk_bf16_f32 v242, v2, v3
	s_waitcnt lgkmcnt(2)
	v_mfma_f32_16x16x32_bf16 v[116:119], v[164:167], v[176:179], v[116:119]
	v_cvt_pk_bf16_f32 v243, v180, v181
	v_mul_f32_e32 v0, v188, v0
	s_mov_b64 s[30:31], -1
	s_waitcnt lgkmcnt(1)
	v_mfma_f32_16x16x32_bf16 v[104:107], v[172:175], v[176:179], v[104:107]
	s_andn2_b64 vcc, exec, s[38:39]
	v_mfma_f32_16x16x32_bf16 v[108:111], v[238:241], v[176:179], v[108:111]
	ds_read2_b64 v[176:179], v186 offset0:168 offset1:172
	v_mfma_f32_16x16x32_bf16 v[184:187], v[148:151], v[12:15], v[48:51]
	ds_read2_b64 v[148:151], v218 offset0:200 offset1:204
	v_mfma_f32_16x16x32_bf16 v[184:187], v[152:155], v[16:19], v[184:187]
	ds_read2_b64 v[152:155], v219 offset0:232 offset1:236
	v_mfma_f32_16x16x32_bf16 v[132:135], v[132:135], v[12:15], v[48:51]
	v_mfma_f32_16x16x32_bf16 v[128:131], v[128:131], v[12:15], v[48:51]
	s_nop 4
	v_fmamk_f32 v180, v184, 0x3e38aa3b, v0
	v_fmamk_f32 v2, v185, 0x3e38aa3b, v0
	v_mfma_f32_16x16x32_bf16 v[124:127], v[124:127], v[12:15], v[48:51]
	v_mfma_f32_16x16x32_bf16 v[132:135], v[144:147], v[16:19], v[132:135]
	v_fmamk_f32 v144, v186, 0x3e38aa3b, v0
	v_fmamk_f32 v145, v187, 0x3e38aa3b, v0
	v_fmac_f32_e32 v0, 0x41800000, v188
	v_mfma_f32_16x16x32_bf16 v[128:131], v[140:143], v[16:19], v[128:131]
	s_nop 2
	s_nop 0
	v_fmamk_f32 v146, v132, 0x3e38aa3b, v0
	v_fmamk_f32 v147, v133, 0x3e38aa3b, v0
	v_mfma_f32_16x16x32_bf16 v[124:127], v[136:139], v[16:19], v[124:127]
	v_fmamk_f32 v181, v134, 0x3e38aa3b, v0
	v_fmamk_f32 v182, v135, 0x3e38aa3b, v0
	v_fmac_f32_e32 v0, 0x41800000, v188
	s_waitcnt lgkmcnt(3)
	v_mfma_f32_16x16x32_bf16 v[112:115], v[168:171], v[242:245], v[112:115]
	v_fmamk_f32 v140, v128, 0x3e38aa3b, v0
	v_fmamk_f32 v141, v129, 0x3e38aa3b, v0
	v_fmamk_f32 v135, v130, 0x3e38aa3b, v0
	s_waitcnt lgkmcnt(2)
	v_mfma_f32_16x16x32_bf16 v[120:123], v[176:179], v[242:245], v[120:123]
	v_fmamk_f32 v136, v131, 0x3e38aa3b, v0
	v_fmac_f32_e32 v0, 0x41800000, v188
	v_fmamk_f32 v137, v124, 0x3e38aa3b, v0
	s_waitcnt lgkmcnt(1)
	v_mfma_f32_16x16x32_bf16 v[116:119], v[148:151], v[242:245], v[116:119]
	v_fmamk_f32 v138, v125, 0x3e38aa3b, v0
	v_fmamk_f32 v134, v126, 0x3e38aa3b, v0
	v_fmac_f32_e32 v0, 0x3e38aa3b, v127
	s_waitcnt lgkmcnt(0)
	v_mfma_f32_16x16x32_bf16 v[104:107], v[152:155], v[242:245], v[104:107]
	v_mov_b32_e32 v139, v2
	v_mfma_f32_16x16x32_bf16 v[108:111], v[238:241], v[242:245], v[108:111]
	s_cbranch_vccnz .LBB0_174
	v_add_u32_e32 v124, s41, v236
	v_add_u32_e32 v2, -15, v124
	v_cmp_gt_u32_e32 vcc, s10, v2
	v_subrev_u32_e32 v3, 48, v124
	v_subrev_u32_e32 v128, 49, v124
	v_cndmask_b32_e32 v2, v226, v180, vcc
	v_cmp_lt_u32_e32 vcc, s13, v183
	v_exp_f32_e32 v125, v2
	v_subrev_u32_e32 v129, 50, v124
	v_cndmask_b32_e32 v2, v226, v139, vcc
	v_exp_f32_e32 v126, v2
	v_subrev_u32_e32 v2, 17, v124
	v_cmp_gt_u32_e32 vcc, s10, v2
	v_subrev_u32_e32 v130, 63, v124
	v_subrev_u32_e32 v131, 64, v124
	v_cndmask_b32_e32 v2, v226, v144, vcc
	v_exp_f32_e32 v127, v2
	v_subrev_u32_e32 v2, 18, v124
	v_cmp_gt_u32_e32 vcc, s10, v2
	v_add_u32_e32 v132, 0xffffffbf, v124
	s_mov_b64 s[30:31], 0
	v_cndmask_b32_e32 v2, v226, v145, vcc
	v_exp_f32_e32 v142, v2
	v_subrev_u32_e32 v2, 31, v124
	v_cmp_gt_u32_e32 vcc, s10, v2
	s_nop 1
	v_cndmask_b32_e32 v2, v226, v146, vcc
	v_exp_f32_e32 v143, v2
	v_subrev_u32_e32 v2, 32, v124
	v_cmp_gt_u32_e32 vcc, s10, v2
	s_nop 1
	v_cndmask_b32_e32 v2, v226, v147, vcc
	v_exp_f32_e32 v183, v2
	v_subrev_u32_e32 v2, 33, v124
	v_cmp_gt_u32_e32 vcc, s10, v2
	s_nop 1
	v_cndmask_b32_e32 v2, v226, v181, vcc
	v_exp_f32_e32 v184, v2
	v_subrev_u32_e32 v2, 34, v124
	v_cmp_gt_u32_e32 vcc, s10, v2
	s_nop 1
	v_cndmask_b32_e32 v2, v226, v182, vcc
	v_exp_f32_e32 v185, v2
	v_subrev_u32_e32 v2, 47, v124
	v_cmp_gt_u32_e32 vcc, s10, v2
	v_add_u32_e32 v124, 0xffffffbe, v124
	s_nop 0
	v_cndmask_b32_e32 v2, v226, v140, vcc
	v_cmp_gt_u32_e32 vcc, s10, v3
	v_exp_f32_e32 v2, v2
	s_nop 0
	v_cndmask_b32_e32 v3, v226, v141, vcc
	v_cmp_gt_u32_e32 vcc, s10, v128
	v_exp_f32_e32 v3, v3
	s_nop 0
	v_cndmask_b32_e32 v128, v226, v135, vcc
	v_cmp_gt_u32_e32 vcc, s10, v129
	v_exp_f32_e32 v128, v128
	s_nop 0
	v_cndmask_b32_e32 v129, v226, v136, vcc
	v_cmp_gt_u32_e32 vcc, s10, v130
	v_exp_f32_e32 v129, v129
	s_nop 0
	v_cndmask_b32_e32 v130, v226, v137, vcc
	v_cmp_gt_u32_e32 vcc, s10, v131
	v_exp_f32_e32 v130, v130
	s_nop 0
	v_cndmask_b32_e32 v131, v226, v138, vcc
	v_cmp_gt_u32_e32 vcc, s10, v132
	v_exp_f32_e32 v131, v131
	s_nop 0
	v_cndmask_b32_e32 v132, v226, v134, vcc
	v_cmp_gt_u32_e32 vcc, s10, v124
	v_exp_f32_e32 v132, v132
	s_nop 0
	v_cndmask_b32_e32 v124, v226, v0, vcc
	v_exp_f32_e32 v133, v124
	v_cvt_pk_bf16_f32 v124, v125, v126
	v_cvt_pk_bf16_f32 v125, v127, v142
	v_cvt_pk_bf16_f32 v126, v143, v183
	v_cvt_pk_bf16_f32 v127, v184, v185

;     ...
;     for (int hk = 0; hk < TK; ++hk) {
;     const u16* cK = sK + stg * FST + hk * TSZ;
;     const u16* cV = cK + 64 * 72;
;     const int k0 = (kt + hk) * 64;
;     if (k0 <= qhi && (qlo - (k0 + 63)) < window) {
;       bool full = (k0 + 63 <= qlo) && (qhi - k0 < window);
;       const bool rowfull = SEL && full;
;       bool selok[NQ];
; #pragma unroll
;       for (int n = 0; n < NQ; ++n) selok[n] = true;
;       if (SEL) {
;         bool all = true;
; #pragma unroll
;         for (int n = 0; n < NQ; ++n) { selok[n] = ((selq[n] >> kt) & 1u) != 0; all = all && selok[n]; }
;         full = full && __all(all);
;       }
;       const int kbase = k0 + quad * 4;
; #pragma unroll
;       for (int mp = 0; mp < NMAP; ++mp) {
; #pragma unroll
;         for (int n = 0; n < NQ; ++n) {
;           f32x4 S[4];
; #pragma unroll
;           for (int mt = 0; mt < 4; ++mt) S[mt] = f32x4{0.f, 0.f, 0.f, 0.f};
; #pragma unroll
;           for (int ks = 0; ks < 2; ++ks) {
;             if (NMAP == 2 && ks != mp) continue;
; #pragma unroll
;             for (int mt = 0; mt < 4; ++mt) {
;               bf16x8 a = *(const bf16x8*)(cK + (mt * 16 + l15) * 64 + (((ks * 4 + quad) ^ ((l15 >> 1) & 7)) * 8));
;               S[mt] = mfma16(a, qf[n][ks], S[mt]);
;             }
;           }
;           bf16x8 pb[2];
;           const float tb = slope2 * (float)(kbase - tq[n]);
;           if (full || rowfull) {
;             sm_step<false>(S, c1, slope2, tb, kbase, tq[n], window, true, pb);
;             if (SEL && !full && !selok[n]) {
;               pb[0] = bf16x8{0, 0, 0, 0, 0, 0, 0, 0}; pb[1] = bf16x8{0, 0, 0, 0, 0, 0, 0, 0};
;             }
;           } else sm_step<true>(S, c1, slope2, tb, kbase, tq[n], window, selok[n], pb);
.LBB0_177:
	s_sub_i32 s29, s40, 63
	s_cmp_gt_i32 s29, s12
	s_cbranch_scc1 .LBB0_188
	s_add_i32 s29, s41, 0xffffff62
	s_cmpk_gt_i32 s29, 0x1ff
	s_cbranch_scc1 .LBB0_188
	v_add_u32_e32 v0, s24, v232
	v_add_u32_e32 v2, v0, v234
	ds_read_b128 v[136:139], v2 offset:18432
	ds_read_b128 v[140:143], v2 offset:20480
	ds_read_b128 v[144:147], v2 offset:22528
	ds_read_b128 v[148:151], v2 offset:24576
	v_add_u32_e32 v0, v0, v235
	ds_read_b128 v[156:159], v0 offset:18432
	ds_read_b128 v[164:167], v0 offset:20480
	ds_read_b128 v[168:171], v0 offset:22528
	ds_read_b128 v[172:175], v0 offset:24576
	s_waitcnt lgkmcnt(7)
	v_mfma_f32_16x16x32_bf16 v[124:127], v[136:139], v[4:7], v[48:51]
	v_add_u32_e32 v249, s40, v237
	v_add_u32_e32 v160, 0xfffff7e1, v249
	v_cvt_f32_i32_e32 v0, v160
	s_waitcnt lgkmcnt(6)
	v_mfma_f32_16x16x32_bf16 v[128:131], v[140:143], v[4:7], v[48:51]
	s_sub_i32 s29, s41, 64
	s_cmpk_lt_i32 s29, 0x200
	s_cselect_b64 s[30:31], -1, 0
	s_waitcnt lgkmcnt(5)
	v_mfma_f32_16x16x32_bf16 v[132:135], v[144:147], v[4:7], v[48:51]
	s_cmp_le_i32 s40, s8
	s_cselect_b64 s[38:39], -1, 0
	s_and_b64 s[30:31], s[38:39], s[30:31]
	s_waitcnt lgkmcnt(4)
	v_mfma_f32_16x16x32_bf16 v[152:155], v[148:151], v[4:7], v[48:51]
	s_mov_b64 s[38:39], -1
	s_and_b64 vcc, exec, s[30:31]
	s_waitcnt lgkmcnt(3)
	v_mfma_f32_16x16x32_bf16 v[124:127], v[156:159], v[8:11], v[124:127]
	s_waitcnt lgkmcnt(2)
	v_mfma_f32_16x16x32_bf16 v[176:179], v[164:167], v[8:11], v[128:131]
	s_waitcnt lgkmcnt(1)
	v_mfma_f32_16x16x32_bf16 v[132:135], v[168:171], v[8:11], v[132:135]
	s_nop 0
	v_mul_f32_e32 v130, v188, v0
	s_nop 1
	v_fmamk_f32 v131, v124, 0x3e38aa3b, v130
	v_add_u32_e32 v0, s41, v236
	s_waitcnt lgkmcnt(0)
	v_mfma_f32_16x16x32_bf16 v[182:185], v[172:175], v[8:11], v[152:155]
	v_fmamk_f32 v2, v125, 0x3e38aa3b, v130
	s_nop 1
	v_fmamk_f32 v153, v126, 0x3e38aa3b, v130
	v_fmamk_f32 v154, v127, 0x3e38aa3b, v130
	v_fmac_f32_e32 v130, 0x41800000, v188
	v_fmamk_f32 v155, v176, 0x3e38aa3b, v130
	v_fmamk_f32 v176, v177, 0x3e38aa3b, v130
	v_fmamk_f32 v177, v178, 0x3e38aa3b, v130
	v_fmamk_f32 v178, v179, 0x3e38aa3b, v130
	v_fmac_f32_e32 v130, 0x41800000, v188
	v_fmamk_f32 v180, v133, 0x3e38aa3b, v130
	v_fmamk_f32 v133, v134, 0x3e38aa3b, v130
	v_fmamk_f32 v179, v132, 0x3e38aa3b, v130
	v_fmamk_f32 v134, v135, 0x3e38aa3b, v130
	v_fmac_f32_e32 v130, 0x41800000, v188
	v_fmamk_f32 v135, v182, 0x3e38aa3b, v130
	v_fmamk_f32 v152, v183, 0x3e38aa3b, v130
	v_fmamk_f32 v132, v184, 0x3e38aa3b, v130
	v_fmac_f32_e32 v130, 0x3e38aa3b, v185
	v_mov_b32_e32 v181, v2
	s_cbranch_vccnz .LBB0_181
	v_add_u32_e32 v248, 0xffffffa1, v0
	v_add_u32_e32 v244, 0xffffff9f, v0
	v_add_u32_e32 v245, 0xffffff9e, v0
	v_add_u32_e32 v246, 0xffffff91, v0
	v_add_u32_e32 v247, 0xffffff90, v0
	v_add_u32_e32 v240, 0xffffff8f, v0
	v_add_u32_e32 v241, 0xffffff8e, v0
	v_add_u32_e32 v242, 0xffffff81, v0
	v_add_u32_e32 v243, 0xffffff80, v0
	v_add_u32_e32 v238, 0xffffff7f, v0
	v_add_u32_e32 v239, 0xffffff7e, v0
	v_cmp_gt_u32_e32 vcc, s10, v248
	v_add_u32_e32 v126, 0xffffff71, v0
	v_add_u32_e32 v127, 0xffffff70, v0
	v_cndmask_b32_e32 v2, v226, v131, vcc
	v_cmp_lt_u32_e32 vcc, s13, v160
	v_exp_f32_e32 v161, v2
	v_add_u32_e32 v128, 0xffffff6f, v0
	v_cndmask_b32_e32 v2, v226, v181, vcc
	v_cmp_gt_u32_e32 vcc, s10, v244
	v_exp_f32_e32 v160, v2
	v_add_u32_e32 v129, 0xffffff6e, v0
	v_cndmask_b32_e32 v2, v226, v153, vcc
	v_cmp_gt_u32_e32 vcc, s10, v245
	v_exp_f32_e32 v162, v2
	v_cvt_pk_bf16_f32 v160, v161, v160
	v_cndmask_b32_e32 v2, v226, v154, vcc
	v_cmp_gt_u32_e32 vcc, s10, v246
	v_exp_f32_e32 v163, v2
	s_mov_b64 s[38:39], 0
	v_cndmask_b32_e32 v2, v226, v155, vcc
	v_cmp_gt_u32_e32 vcc, s10, v247
	v_exp_f32_e32 v182, v2
	v_cvt_pk_bf16_f32 v161, v162, v163
	v_cndmask_b32_e32 v2, v226, v176, vcc
	v_cmp_gt_u32_e32 vcc, s10, v240
	v_exp_f32_e32 v183, v2
	s_nop 0
	v_cndmask_b32_e32 v2, v226, v177, vcc
	v_cmp_gt_u32_e32 vcc, s10, v241
	v_exp_f32_e32 v184, v2
	v_cvt_pk_bf16_f32 v162, v182, v183
	v_cndmask_b32_e32 v2, v226, v178, vcc
	v_cmp_gt_u32_e32 vcc, s10, v242
	v_exp_f32_e32 v185, v2
	s_nop 0
	v_cndmask_b32_e32 v2, v226, v179, vcc
	v_cmp_gt_u32_e32 vcc, s10, v243
	v_exp_f32_e32 v2, v2
	v_cvt_pk_bf16_f32 v163, v184, v185
	v_cndmask_b32_e32 v3, v226, v180, vcc
	v_cmp_gt_u32_e32 vcc, s10, v238
	v_exp_f32_e32 v3, v3
	s_nop 0
	v_cndmask_b32_e32 v124, v226, v133, vcc
	v_cmp_gt_u32_e32 vcc, s10, v239
	v_exp_f32_e32 v124, v124
	s_nop 0
	v_cndmask_b32_e32 v125, v226, v134, vcc
	v_cmp_gt_u32_e32 vcc, s10, v126
	v_exp_f32_e32 v125, v125
	s_nop 0
	v_cndmask_b32_e32 v126, v226, v135, vcc
	v_cmp_gt_u32_e32 vcc, s10, v127
	v_exp_f32_e32 v126, v126
	s_nop 0
	v_cndmask_b32_e32 v127, v226, v152, vcc
	v_cmp_gt_u32_e32 vcc, s10, v128
	v_exp_f32_e32 v127, v127
	s_nop 0
	v_cndmask_b32_e32 v128, v226, v132, vcc
	v_cmp_gt_u32_e32 vcc, s10, v129
	v_exp_f32_e32 v128, v128
	s_nop 0
	v_cndmask_b32_e32 v129, v226, v130, vcc
	v_exp_f32_e32 v129, v129

;     ...
;         for (int n = 0; n < NQ; ++n) {
;           f32x4 S[4];
; #pragma unroll
;           for (int mt = 0; mt < 4; ++mt) S[mt] = f32x4{0.f, 0.f, 0.f, 0.f};
; #pragma unroll
;           for (int ks = 0; ks < 2; ++ks) {
;             if (NMAP == 2 && ks != mp) continue;
; #pragma unroll
;             for (int mt = 0; mt < 4; ++mt) {
;               bf16x8 a = *(const bf16x8*)(cK + (mt * 16 + l15) * 64 + (((ks * 4 + quad) ^ ((l15 >> 1) & 7)) * 8));
;               S[mt] = mfma16(a, qf[n][ks], S[mt]);
;             }
;           }
;           bf16x8 pb[2];
;           const float tb = slope2 * (float)(kbase - tq[n]);
;           if (full || rowfull) {
;             sm_step<false>(S, c1, slope2, tb, kbase, tq[n], window, true, pb);
;             if (SEL && !full && !selok[n]) {
;               pb[0] = bf16x8{0, 0, 0, 0, 0, 0, 0, 0}; pb[1] = bf16x8{0, 0, 0, 0, 0, 0, 0, 0};
;             }
;           } else sm_step<true>(S, c1, slope2, tb, kbase, tq[n], window, selok[n], pb);
; #pragma unroll
;           for (int k2 = 0; k2 < 2; ++k2) {
; #pragma unroll
;             for (int dt = 0; dt < 4; ++dt) {
;               bf16x8 a = vt_frag(cV, dt, k2, l15, quad);
;               O[mp * NQ + n][dt] = mfma16(a, pb[k2], O[mp * NQ + n][dt]);
;             }
;             L[mp * NQ + n] = mfma16(ones, pb[k2], L[mp * NQ + n]);
;           }
.LBB0_183:
	v_lshlrev_b32_e32 v130, 1, v231
	v_cvt_pk_bf16_f32 v218, v2, v3
	v_add3_u32 v2, s24, v130, v233
	v_add_u32_e32 v3, 0x6800, v2
	v_add_u32_e32 v176, 0x7000, v2
	v_add_u32_e32 v180, 0x7800, v2
	v_add_u32_e32 v2, 0x8000, v2
	v_cvt_pk_bf16_f32 v219, v124, v125
	v_cvt_pk_bf16_f32 v220, v126, v127
	v_cvt_pk_bf16_f32 v221, v128, v129
	ds_read2_b64 v[124:127], v3 offset0:128 offset1:132
	ds_read2_b64 v[128:131], v176 offset0:160 offset1:164
	ds_read2_b64 v[132:135], v180 offset0:192 offset1:196
	ds_read2_b64 v[152:155], v2 offset0:224 offset1:228
	s_xor_b64 s[38:39], s[30:31], -1
	s_mov_b32 s30, s28
	s_mov_b32 s31, s28
	s_mov_b32 s29, s28
	v_mov_b64_e32 v[224:225], s[30:31]
	v_mov_b64_e32 v[222:223], s[28:29]
	s_waitcnt lgkmcnt(3)
	v_mfma_f32_16x16x32_bf16 v[112:115], v[124:127], v[160:163], v[112:115]
	ds_read2_b64 v[176:179], v176 offset0:168 offset1:172
	ds_read2_b64 v[180:183], v180 offset0:200 offset1:204
	ds_read2_b64 v[184:187], v2 offset0:232 offset1:236
	s_waitcnt lgkmcnt(5)
	v_mfma_f32_16x16x32_bf16 v[120:123], v[128:131], v[160:163], v[120:123]
	s_mov_b64 s[30:31], -1
	s_andn2_b64 vcc, exec, s[38:39]
	s_waitcnt lgkmcnt(4)
	v_mfma_f32_16x16x32_bf16 v[116:119], v[132:135], v[160:163], v[116:119]
	s_waitcnt lgkmcnt(3)
	v_mfma_f32_16x16x32_bf16 v[104:107], v[152:155], v[160:163], v[104:107]
	v_mfma_f32_16x16x32_bf16 v[108:111], v[222:225], v[160:163], v[108:111]
	ds_read2_b64 v[160:163], v3 offset0:136 offset1:140
	v_mfma_f32_16x16x32_bf16 v[136:139], v[136:139], v[12:15], v[48:51]
	v_mfma_f32_16x16x32_bf16 v[140:143], v[140:143], v[12:15], v[48:51]
	v_mfma_f32_16x16x32_bf16 v[144:147], v[144:147], v[12:15], v[48:51]
	v_mfma_f32_16x16x32_bf16 v[148:151], v[148:151], v[12:15], v[48:51]
	v_mfma_f32_16x16x32_bf16 v[156:159], v[156:159], v[16:19], v[136:139]
	s_nop 3
	v_add_u32_e32 v136, 0xfffff7d1, v249
	v_cvt_f32_i32_e32 v2, v136
	v_mfma_f32_16x16x32_bf16 v[138:141], v[164:167], v[16:19], v[140:143]
	v_mfma_f32_16x16x32_bf16 v[142:145], v[168:171], v[16:19], v[144:147]
	v_mfma_f32_16x16x32_bf16 v[168:171], v[172:175], v[16:19], v[148:151]
	s_nop 1
	v_mul_f32_e32 v146, v188, v2
	v_fmamk_f32 v147, v156, 0x3e38aa3b, v146
	v_fmamk_f32 v2, v157, 0x3e38aa3b, v146
	s_waitcnt lgkmcnt(0)
	v_mfma_f32_16x16x32_bf16 v[112:115], v[160:163], v[218:221], v[112:115]
	v_fmamk_f32 v148, v158, 0x3e38aa3b, v146
	v_fmamk_f32 v149, v159, 0x3e38aa3b, v146
	v_fmac_f32_e32 v146, 0x41800000, v188
	v_mfma_f32_16x16x32_bf16 v[120:123], v[176:179], v[218:221], v[120:123]
	v_fmamk_f32 v150, v138, 0x3e38aa3b, v146
	v_fmamk_f32 v151, v139, 0x3e38aa3b, v146
	v_fmamk_f32 v156, v140, 0x3e38aa3b, v146
	v_mfma_f32_16x16x32_bf16 v[116:119], v[180:183], v[218:221], v[116:119]
	v_fmamk_f32 v157, v141, 0x3e38aa3b, v146
	v_fmac_f32_e32 v146, 0x41800000, v188
	v_fmamk_f32 v158, v142, 0x3e38aa3b, v146
	v_mfma_f32_16x16x32_bf16 v[104:107], v[184:187], v[218:221], v[104:107]
	v_fmamk_f32 v159, v143, 0x3e38aa3b, v146
	v_fmamk_f32 v164, v144, 0x3e38aa3b, v146
	v_fmamk_f32 v165, v145, 0x3e38aa3b, v146
	v_mfma_f32_16x16x32_bf16 v[108:111], v[222:225], v[218:221], v[108:111]
	v_fmac_f32_e32 v146, 0x41800000, v188
	v_fmamk_f32 v166, v168, 0x3e38aa3b, v146
	v_fmamk_f32 v168, v169, 0x3e38aa3b, v146
	v_fmamk_f32 v167, v170, 0x3e38aa3b, v146
	v_fmac_f32_e32 v146, 0x3e38aa3b, v171
	v_mov_b32_e32 v169, v2
	s_cbranch_vccnz .LBB0_185
	v_add_u32_e32 v2, 0xffffffb1, v0
	v_cmp_gt_u32_e32 vcc, s10, v2
	s_mov_b64 s[30:31], 0
	s_nop 0
	v_cndmask_b32_e32 v2, v226, v147, vcc
	v_cmp_lt_u32_e32 vcc, s13, v136
	v_exp_f32_e32 v137, v2
	s_nop 0
	v_cndmask_b32_e32 v2, v226, v169, vcc
	v_exp_f32_e32 v136, v2
	v_add_u32_e32 v2, 0xffffffaf, v0
	v_cmp_gt_u32_e32 vcc, s10, v2
	v_cvt_pk_bf16_f32 v136, v137, v136
	s_nop 0
	v_cndmask_b32_e32 v2, v226, v148, vcc
	v_exp_f32_e32 v138, v2
	v_add_u32_e32 v2, 0xffffffae, v0
	v_cmp_gt_u32_e32 vcc, s10, v2
	v_add_u32_e32 v0, 0xffffffa0, v0
	s_nop 0
	v_cndmask_b32_e32 v2, v226, v149, vcc
	v_cmp_gt_u32_e32 vcc, s10, v248
	v_exp_f32_e32 v139, v2
	s_nop 0
	v_cndmask_b32_e32 v2, v226, v150, vcc
	v_cmp_gt_u32_e32 vcc, s10, v0
	v_exp_f32_e32 v170, v2
	v_cvt_pk_bf16_f32 v137, v138, v139
	v_cndmask_b32_e32 v0, v226, v151, vcc
	v_cmp_gt_u32_e32 vcc, s10, v244
	v_exp_f32_e32 v0, v0
	s_nop 0
	v_cndmask_b32_e32 v2, v226, v156, vcc
	v_cmp_gt_u32_e32 vcc, s10, v245
	v_exp_f32_e32 v171, v2
	v_cvt_pk_bf16_f32 v138, v170, v0
	v_cndmask_b32_e32 v2, v226, v157, vcc
	v_cmp_gt_u32_e32 vcc, s10, v246
	v_exp_f32_e32 v172, v2
	s_nop 0
	v_cndmask_b32_e32 v2, v226, v158, vcc
	v_cmp_gt_u32_e32 vcc, s10, v247
	v_exp_f32_e32 v2, v2
	v_cvt_pk_bf16_f32 v139, v171, v172
	v_cndmask_b32_e32 v3, v226, v159, vcc
	v_cmp_gt_u32_e32 vcc, s10, v240
	v_exp_f32_e32 v3, v3
	s_nop 0
	v_cndmask_b32_e32 v140, v226, v164, vcc
	v_cmp_gt_u32_e32 vcc, s10, v241
	v_exp_f32_e32 v140, v140
	s_nop 0
	v_cndmask_b32_e32 v141, v226, v165, vcc
	v_cmp_gt_u32_e32 vcc, s10, v242
	v_exp_f32_e32 v141, v141
	s_nop 0
	v_cndmask_b32_e32 v142, v226, v166, vcc
	v_cmp_gt_u32_e32 vcc, s10, v243
	v_exp_f32_e32 v142, v142
	s_nop 0
	v_cndmask_b32_e32 v143, v226, v168, vcc
	v_cmp_gt_u32_e32 vcc, s10, v238
	v_exp_f32_e32 v143, v143
	s_nop 0
	v_cndmask_b32_e32 v144, v226, v167, vcc
	v_cmp_gt_u32_e32 vcc, s10, v239
	v_exp_f32_e32 v144, v144
	s_nop 0
	v_cndmask_b32_e32 v145, v226, v146, vcc
	v_exp_f32_e32 v145, v145

; __global__ void __launch_bounds__(256, 2) hybrid_megakernel(Params p, int ph_lo, int ph_hi) {
;   __shared__ __attribute__((aligned(16))) unsigned char smem[SM_TOTAL];
	.amdhsa_kernel _Z17hybrid_megakernel6Paramsii
		.amdhsa_group_segment_fixed_size 78096
		.amdhsa_private_segment_fixed_size 0
		.amdhsa_kernarg_size 416
		.amdhsa_user_sgpr_count 2
		.amdhsa_user_sgpr_dispatch_ptr 0
		.amdhsa_user_sgpr_queue_ptr 0
		.amdhsa_user_sgpr_kernarg_segment_ptr 1
		.amdhsa_user_sgpr_dispatch_id 0
		.amdhsa_user_sgpr_kernarg_preload_length 0
		.amdhsa_user_sgpr_kernarg_preload_offset 0
		.amdhsa_user_sgpr_private_segment_size 0
		.amdhsa_uses_dynamic_stack 0
		.amdhsa_enable_private_segment 0
		.amdhsa_system_sgpr_workgroup_id_x 1
		.amdhsa_system_sgpr_workgroup_id_y 0
		.amdhsa_system_sgpr_workgroup_id_z 0
		.amdhsa_system_sgpr_workgroup_info 0
		.amdhsa_system_vgpr_workitem_id 2
		.amdhsa_next_free_vgpr 256
		.amdhsa_next_free_sgpr 100
		.amdhsa_accum_offset 256
		.amdhsa_reserve_vcc 1
		.amdhsa_float_round_mode_32 0
		.amdhsa_float_round_mode_16_64 0
		.amdhsa_float_denorm_mode_32 3
		.amdhsa_float_denorm_mode_16_64 3
		.amdhsa_dx10_clamp 1
		.amdhsa_ieee_mode 1
		.amdhsa_fp16_overflow 0
		.amdhsa_tg_split 0
		.amdhsa_exception_fp_ieee_invalid_op 0
		.amdhsa_exception_fp_denorm_src 0
		.amdhsa_exception_fp_ieee_div_zero 0
		.amdhsa_exception_fp_ieee_overflow 0
		.amdhsa_exception_fp_ieee_underflow 0
		.amdhsa_exception_fp_ieee_inexact 0
		.amdhsa_exception_int_div_zero 0
	.end_amdhsa_kernel

; __global__ void __launch_bounds__(256, 2) hybrid_megakernel(Params p, int ph_lo, int ph_hi) {
;   __shared__ __attribute__((aligned(16))) unsigned char smem[SM_TOTAL];
amdhsa.kernels:
  - .agpr_count:     0
    .args:
      - .offset:         0
        .size:           152
        .value_kind:     by_value
      - .offset:         152
        .size:           4
        .value_kind:     by_value
      - .offset:         156
        .size:           4
        .value_kind:     by_value
      - .offset:         160
        .size:           4
        .value_kind:     hidden_block_count_x
      - .offset:         164
        .size:           4
        .value_kind:     hidden_block_count_y
      - .offset:         168
        .size:           4
        .value_kind:     hidden_block_count_z
      - .offset:         172
        .size:           2
        .value_kind:     hidden_group_size_x
      - .offset:         174
        .size:           2
        .value_kind:     hidden_group_size_y
      - .offset:         176
        .size:           2
        .value_kind:     hidden_group_size_z
      - .offset:         178
        .size:           2
        .value_kind:     hidden_remainder_x
      - .offset:         180
        .size:           2
        .value_kind:     hidden_remainder_y
      - .offset:         182
        .size:           2
        .value_kind:     hidden_remainder_z
      - .offset:         200
        .size:           8
        .value_kind:     hidden_global_offset_x
      - .offset:         208
        .size:           8
        .value_kind:     hidden_global_offset_y
      - .offset:         216
        .size:           8
        .value_kind:     hidden_global_offset_z
      - .offset:         224
        .size:           2
        .value_kind:     hidden_grid_dims
      - .offset:         248
        .size:           8
        .value_kind:     hidden_multigrid_sync_arg
    .group_segment_fixed_size: 78096
    .kernarg_segment_align: 8
    .kernarg_segment_size: 416
    .language:       OpenCL C
    .language_version:
      - 2
      - 0
    .max_flat_workgroup_size: 256
    .name:           _Z17hybrid_megakernel6Paramsii
    .private_segment_fixed_size: 0
    .sgpr_count:     106
    .sgpr_spill_count: 159
    .symbol:         _Z17hybrid_megakernel6Paramsii.kd
    .uniform_work_group_size: 1
    .uses_dynamic_stack: false
    .vgpr_count:     256
    .vgpr_spill_count: 0
    .wavefront_size: 64
